# GLA pass A/C items: staging loads (w_a2, b_a, V^T/K/Q tiles, chunk states) issued together at the item head with distinct registers and counted vmcnt instead of one vmcnt(0) per load
# speedup vs baseline: 1.4465x; 1.0280x over previous
.LBB0_162:
	s_and_b64 vcc, exec, s[0:1]
	s_cbranch_vccz .LBB0_137
	v_mov_b32_e32 v22, v177
	s_movk_i32 s0, 0xffe0
	v_ashrrev_i32_e32 v0, 2, v22
	v_bfi_b32 v16, s0, v0, v22
	s_ashr_i32 s0, s2, 31
	s_lshr_b32 s0, s0, 28
	s_add_i32 s0, s2, s0
	s_ashr_i32 s3, s0, 4
	s_and_b32 s0, s0, -16
	s_sub_i32 s7, s2, s0
	s_lshr_b32 s0, s7, 2
	s_lshl_b32 s6, s3, 6
	s_mulk_i32 s0, 0x2080
	s_add_i32 s0, s0, s6
	s_and_b32 s2, s7, 3
	s_mul_hi_i32 s1, s0, 0x2c30
	s_mulk_i32 s0, 0x2c30
	v_ashrrev_i32_e32 v32, 6, v22
	s_add_u32 s0, s56, s0
	s_mulk_i32 s7, 0x82
	v_bfe_u32 v33, v22, 5, 1
	v_and_b32_e32 v25, 1, v32
	s_addc_u32 s1, s57, s1
	s_add_i32 s8, s7, s3
	v_lshl_or_b32 v23, v25, 1, v33
	s_ashr_i32 s9, s8, 31
	s_lshl_b64 s[10:11], s[8:9], 6
	v_lshlrev_b32_e32 v24, 4, v23
	v_or_b32_e32 v0, s10, v24
	v_mov_b32_e32 v1, s11
	v_lshlrev_b64 v[8:9], 8, v[0:1]
	v_lshlrev_b32_e32 v0, 2, v22
	v_and_b32_e32 v1, 3, v22
	v_and_or_b32 v0, v0, 16, v1
	v_lshrrev_b32_e32 v1, 1, v22
	v_and_b32_e32 v1, 12, v1
	v_lshlrev_b32_e32 v2, 5, v25
	v_or3_b32 v0, v0, v1, v2
	v_mul_u32_u24_e32 v0, 0x1618, v0
	v_lshlrev_b32_e32 v178, 1, v0
	v_lshl_add_u64 v[0:1], s[0:1], 0, v[178:179]
	v_lshlrev_b32_e32 v178, 4, v33
	v_lshl_add_u64 v[0:1], v[0:1], 0, v[178:179]
	v_lshlrev_b32_e32 v178, 13, v33
	v_ashrrev_i32_e32 v17, 31, v16
	s_waitcnt lgkmcnt(0)
	v_lshl_add_u64 v[4:5], s[18:19], 0, v[178:179]
	s_lshl_b32 s16, s2, 8
	v_add_co_u32_e32 v0, vcc, s38, v0
	v_lshl_add_u64 v[4:5], v[4:5], 0, s[16:17]
	v_lshlrev_b64 v[18:19], 2, v[16:17]
	v_addc_co_u32_e32 v1, vcc, 0, v1, vcc
	v_lshl_add_u64 v[6:7], v[4:5], 0, v[18:19]
	s_barrier
	global_load_dwordx4 v[0:3], v[0:1], off offset:2064
	s_nop 0
	global_load_dword v80, v[6:7], off
	global_load_dword v81, v[6:7], off offset:1024
	s_lshl_b32 s3, s2, 6
	s_or_b32 s3, s3, s22
	v_add_u32_e32 v26, s3, v16
	v_readlane_b32 s68, v245, 2
	v_ashrrev_i32_e32 v27, 31, v26
	v_readlane_b32 s80, v245, 14
	v_readlane_b32 s81, v245, 15
	v_readlane_b32 s24, v245, 36
	v_readlane_b32 s25, v245, 37
	v_lshl_add_u64 v[26:27], v[26:27], 2, s[80:81]
	s_mov_b32 s3, 0x3d800000
	v_lshl_add_u64 v[20:21], s[24:25], 0, v[8:9]
	v_and_b32_e32 v30, 63, v22
	s_mov_b64 s[24:25], 0x1410
	s_movk_i32 s7, 0x480
	s_lshl_b32 s2, s2, 7
	v_readlane_b32 s26, v245, 38
	v_readlane_b32 s27, v245, 39
	v_readlane_b32 s69, v245, 3
	v_readlane_b32 s70, v245, 4
	v_readlane_b32 s71, v245, 5
	v_readlane_b32 s72, v245, 6
	v_readlane_b32 s73, v245, 7
	v_readlane_b32 s74, v245, 8
	v_readlane_b32 s75, v245, 9
	v_readlane_b32 s76, v245, 10
	v_readlane_b32 s77, v245, 11
	v_readlane_b32 s78, v245, 12
	v_readlane_b32 s79, v245, 13
	v_readlane_b32 s82, v245, 16
	v_readlane_b32 s83, v245, 17
	global_load_dword v82, v[6:7], off offset:2048
	global_load_dword v83, v[6:7], off offset:3072
	v_add_co_u32_e32 v10, vcc, s38, v6
	s_nop 1
	v_addc_co_u32_e32 v11, vcc, 0, v7, vcc
	global_load_dword v84, v[10:11], off
	global_load_dword v85, v[10:11], off offset:1024
	global_load_dword v86, v[10:11], off offset:2048
	global_load_dword v87, v[10:11], off offset:3072
	global_load_dword v31, v[26:27], off
	v_and_b32_e32 v88, 63, v22
	v_mul_u32_u24_e32 v88, 0x1618, v88
	v_lshlrev_b32_e32 v88, 1, v88
	v_lshlrev_b32_e32 v89, 4, v32
	v_add3_u32 v88, v88, v89, s16
	v_add_u32_e32 v88, 0x1410, v88
	v_mov_b32_e32 v89, v179
	v_lshl_add_u64 v[88:89], s[0:1], 0, v[88:89]
	global_load_dwordx4 v[96:99], v[88:89], off
	global_load_dwordx4 v[100:103], v[88:89], off offset:64
	global_load_dwordx4 v[104:107], v[88:89], off offset:128
	global_load_dwordx4 v[108:111], v[88:89], off offset:192
	v_ashrrev_i32_e32 v90, 3, v22
	v_mul_u32_u24_e32 v90, 0x2c30, v90
	v_lshlrev_b32_e32 v91, 4, v22
	v_and_b32_e32 v91, 0x70, v91
	v_add3_u32 v90, v90, v91, s2
	v_add_u32_e32 v90, 0x1210, v90
	v_mov_b32_e32 v91, v179
	v_lshl_add_u64 v[92:93], s[0:1], 0, v[90:91]
	global_load_dwordx4 v[112:115], v[92:93], off
	v_add_u32_e32 v90, 0x58600, v90
	v_lshl_add_u64 v[92:93], s[0:1], 0, v[90:91]
	global_load_dwordx4 v[116:119], v[92:93], off
	s_waitcnt vmcnt(7)
	v_cvt_pk_bf16_f32 v4, v80, v81
	v_cvt_pk_bf16_f32 v5, v82, v83
	v_cvt_pk_bf16_f32 v6, v84, v85
	v_cvt_pk_bf16_f32 v7, v86, v87
	s_nop 1
	v_mfma_f32_32x32x16_bf16 v[0:15], v[0:3], v[4:7], 0
	s_waitcnt vmcnt(6)
	s_nop 10
	v_add_f32_e32 v0, v31, v0
	v_min_f32_e32 v26, 0, v0
	v_mul_f32_e64 v0, |v0|, s98
	v_exp_f32_e32 v0, v0
	s_nop 0
	v_add_f32_e32 v0, 1.0, v0
	v_log_f32_e32 v0, v0
	s_nop 0
	v_fmac_f32_e32 v26, 0xbf317218, v0
	v_add_f32_e32 v0, v31, v1
	v_min_f32_e32 v1, 0, v0
	v_mul_f32_e64 v0, |v0|, s98
	v_exp_f32_e32 v0, v0
	v_fma_f32 v26, v26, s3, 0
	s_mov_b32 s3, s17
	v_add_f32_e32 v0, 1.0, v0
	v_log_f32_e32 v0, v0
	s_nop 0
	v_fmac_f32_e32 v1, 0xbf317218, v0
	v_add_f32_e32 v0, v31, v2
	v_fmamk_f32 v27, v1, 0x3d800000, v26
	v_min_f32_e32 v1, 0, v0
	v_mul_f32_e64 v0, |v0|, s98
	v_exp_f32_e32 v0, v0
	v_lshlrev_b32_e32 v2, 3, v32
	v_add_f32_e32 v0, 1.0, v0
	v_log_f32_e32 v0, v0
	s_nop 0
	v_fmac_f32_e32 v1, 0xbf317218, v0
	v_add_f32_e32 v0, v31, v3
	v_fmamk_f32 v28, v1, 0x3d800000, v27
	v_min_f32_e32 v1, 0, v0
	v_mul_f32_e64 v0, |v0|, s98
	v_exp_f32_e32 v0, v0
	v_ashrrev_i32_e32 v3, 31, v2
	v_add_f32_e32 v0, 1.0, v0
	v_log_f32_e32 v0, v0
	s_nop 0
	v_fmac_f32_e32 v1, 0xbf317218, v0
	v_add_f32_e32 v0, v31, v4
	v_fmamk_f32 v29, v1, 0x3d800000, v28
	v_min_f32_e32 v1, 0, v0
	v_mul_f32_e64 v0, |v0|, s98
	v_exp_f32_e32 v0, v0
	s_nop 0
	v_add_f32_e32 v0, 1.0, v0
	v_log_f32_e32 v0, v0
	s_nop 0
	v_fmac_f32_e32 v1, 0xbf317218, v0
	v_add_f32_e32 v0, v31, v5
	v_fmamk_f32 v4, v1, 0x3d800000, v29
	v_min_f32_e32 v1, 0, v0
	v_mul_f32_e64 v0, |v0|, s98
	v_exp_f32_e32 v0, v0
	s_nop 0
	v_add_f32_e32 v0, 1.0, v0
	v_log_f32_e32 v0, v0
	s_nop 0
	v_fmac_f32_e32 v1, 0xbf317218, v0
	v_add_f32_e32 v0, v31, v6
	v_fmamk_f32 v5, v1, 0x3d800000, v4
	v_min_f32_e32 v1, 0, v0
	v_mul_f32_e64 v0, |v0|, s98
	v_exp_f32_e32 v0, v0
	s_nop 0
	v_add_f32_e32 v0, 1.0, v0
	v_log_f32_e32 v0, v0
	s_nop 0
	v_fmac_f32_e32 v1, 0xbf317218, v0
	v_add_f32_e32 v0, v31, v7
	v_fmamk_f32 v6, v1, 0x3d800000, v5
	v_min_f32_e32 v1, 0, v0
	v_mul_f32_e64 v0, |v0|, s98
	v_exp_f32_e32 v0, v0
	s_nop 0
	v_add_f32_e32 v0, 1.0, v0
	v_log_f32_e32 v0, v0
	s_nop 0
	v_fmac_f32_e32 v1, 0xbf317218, v0
	v_add_f32_e32 v0, v31, v8
	v_fmamk_f32 v7, v1, 0x3d800000, v6
	v_min_f32_e32 v1, 0, v0
	v_mul_f32_e64 v0, |v0|, s98
	v_exp_f32_e32 v0, v0
	s_nop 0
	v_add_f32_e32 v0, 1.0, v0
	v_log_f32_e32 v0, v0
	s_nop 0
	v_fmac_f32_e32 v1, 0xbf317218, v0
	v_add_f32_e32 v0, v31, v9
	v_fmamk_f32 v8, v1, 0x3d800000, v7
	v_min_f32_e32 v1, 0, v0
	v_mul_f32_e64 v0, |v0|, s98
	v_exp_f32_e32 v0, v0
	s_nop 0
	v_add_f32_e32 v0, 1.0, v0
	v_log_f32_e32 v0, v0
	s_nop 0
	v_fmac_f32_e32 v1, 0xbf317218, v0
	v_add_f32_e32 v0, v31, v10
	v_fmamk_f32 v9, v1, 0x3d800000, v8
	v_min_f32_e32 v1, 0, v0
	v_mul_f32_e64 v0, |v0|, s98
	v_exp_f32_e32 v0, v0
	s_nop 0
	v_add_f32_e32 v0, 1.0, v0
	v_log_f32_e32 v0, v0
	s_nop 0
	v_fmac_f32_e32 v1, 0xbf317218, v0
	v_add_f32_e32 v0, v31, v11
	v_fmamk_f32 v10, v1, 0x3d800000, v9
	v_min_f32_e32 v1, 0, v0
	v_mul_f32_e64 v0, |v0|, s98
	v_exp_f32_e32 v0, v0
	s_nop 0
	v_add_f32_e32 v0, 1.0, v0
	v_log_f32_e32 v0, v0
	s_nop 0
	v_fmac_f32_e32 v1, 0xbf317218, v0
	v_add_f32_e32 v0, v31, v12
	v_fmamk_f32 v11, v1, 0x3d800000, v10
	v_min_f32_e32 v1, 0, v0
	v_mul_f32_e64 v0, |v0|, s98
	v_exp_f32_e32 v0, v0
	s_nop 0
	v_add_f32_e32 v0, 1.0, v0
	v_log_f32_e32 v0, v0
	s_nop 0
	v_fmac_f32_e32 v1, 0xbf317218, v0
	v_add_f32_e32 v0, v31, v13
	v_fmamk_f32 v12, v1, 0x3d800000, v11
	v_min_f32_e32 v1, 0, v0
	v_mul_f32_e64 v0, |v0|, s98
	v_exp_f32_e32 v0, v0
	s_nop 0
	v_add_f32_e32 v0, 1.0, v0
	v_log_f32_e32 v0, v0
	s_nop 0
	v_fmac_f32_e32 v1, 0xbf317218, v0
	v_add_f32_e32 v0, v31, v14
	v_fmamk_f32 v13, v1, 0x3d800000, v12
	v_min_f32_e32 v1, 0, v0
	v_mul_f32_e64 v0, |v0|, s98
	v_exp_f32_e32 v0, v0
	s_nop 0
	v_add_f32_e32 v0, 1.0, v0
	v_log_f32_e32 v0, v0
	s_nop 0
	v_fmac_f32_e32 v1, 0xbf317218, v0
	v_add_f32_e32 v0, v31, v15
	v_fmamk_f32 v14, v1, 0x3d800000, v13
	v_min_f32_e32 v1, 0, v0
	v_mul_f32_e64 v0, |v0|, s98
	v_exp_f32_e32 v0, v0
	v_lshlrev_b32_e32 v15, 2, v16
	v_add_f32_e32 v0, 1.0, v0
	v_log_f32_e32 v0, v0
	s_nop 0
	v_fmac_f32_e32 v1, 0xbf317218, v0
	v_fmamk_f32 v31, v1, 0x3d800000, v14
	v_lshl_add_u32 v0, v23, 8, v15
	ds_write_b32 v0, v31 offset:64512
	v_mul_u32_u24_e32 v0, 0x1618, v30
	v_lshlrev_b32_e32 v178, 1, v0
	v_lshl_add_u64 v[0:1], s[0:1], 0, v[178:179]
	v_lshl_add_u64 v[0:1], v[0:1], 0, s[16:17]
	v_lshl_add_u64 v[0:1], v[2:3], 1, v[0:1]
	v_lshl_add_u64 v[34:35], v[0:1], 0, s[24:25]
	v_add_co_u32_e32 v0, vcc, s38, v0
	v_mul_lo_u32 v2, v32, s7
	s_nop 0
	v_addc_co_u32_e32 v1, vcc, 0, v1, vcc
	v_lshl_or_b32 v30, v30, 1, v2
	s_waitcnt vmcnt(5)
	ds_write_b16 v30, v96 offset:18432
	ds_write_b16_d16_hi v30, v96 offset:18576
	ds_write_b16 v30, v97 offset:18720
	ds_write_b16_d16_hi v30, v97 offset:18864
	ds_write_b16 v30, v98 offset:19008
	ds_write_b16_d16_hi v30, v98 offset:19152
	ds_write_b16 v30, v99 offset:19296
	ds_write_b16_d16_hi v30, v99 offset:19440
	s_waitcnt vmcnt(4)
	ds_write_b16 v30, v100 offset:23040
	ds_write_b16_d16_hi v30, v100 offset:23184
	ds_write_b16 v30, v101 offset:23328
	ds_write_b16_d16_hi v30, v101 offset:23472
	ds_write_b16 v30, v102 offset:23616
	ds_write_b16_d16_hi v30, v102 offset:23760
	ds_write_b16 v30, v103 offset:23904
	ds_write_b16_d16_hi v30, v103 offset:24048
	s_waitcnt vmcnt(3)
	ds_write_b16 v30, v104 offset:27648
	ds_write_b16_d16_hi v30, v104 offset:27792
	ds_write_b16 v30, v105 offset:27936
	ds_write_b16_d16_hi v30, v105 offset:28080
	ds_write_b16 v30, v106 offset:28224
	ds_write_b16_d16_hi v30, v106 offset:28368
	ds_write_b16 v30, v107 offset:28512
	ds_write_b16_d16_hi v30, v107 offset:28656
	s_waitcnt vmcnt(2)
	ds_write_b16 v30, v108 offset:32256
	ds_write_b16_d16_hi v30, v108 offset:32400
	ds_write_b16 v30, v109 offset:32544
	ds_write_b16_d16_hi v30, v109 offset:32688
	ds_write_b16 v30, v110 offset:32832
	ds_write_b16_d16_hi v30, v110 offset:32976
	ds_write_b16 v30, v111 offset:33120
	ds_write_b16_d16_hi v30, v111 offset:33264
	v_lshlrev_b32_e32 v0, 4, v22
	v_ashrrev_i32_e32 v30, 3, v22
	v_mov_b64_e32 v[34:35], s[0:1]
	v_and_b32_e32 v178, 0x70, v0
	v_mad_i64_i32 v[0:1], s[0:1], v30, s13, v[34:35]
	v_lshl_add_u64 v[0:1], v[0:1], 0, s[2:3]
	v_lshl_add_u64 v[0:1], v[0:1], 0, v[178:179]
	v_add_co_u32_e32 v0, vcc, s38, v0
	v_mad_u64_u32 v[36:37], s[0:1], v30, s12, v[178:179]
	s_nop 0
	v_addc_co_u32_e32 v1, vcc, 0, v1, vcc
	s_waitcnt vmcnt(1)
	ds_write_b128 v36, v[112:115] offset:9216
	v_add_u32_e32 v0, 0x100, v22
	v_ashrrev_i32_e32 v30, 3, v0
	v_mad_i64_i32 v[0:1], s[0:1], v30, s13, v[34:35]
	v_lshl_add_u64 v[0:1], v[0:1], 0, s[2:3]
	v_lshl_add_u64 v[0:1], v[0:1], 0, v[178:179]
	v_add_co_u32_e32 v0, vcc, s38, v0
	v_mad_u64_u32 v[34:35], s[0:1], v30, s12, v[178:179]
	s_nop 0
	v_addc_co_u32_e32 v1, vcc, 0, v1, vcc
	v_cmp_eq_u32_e32 vcc, 0, v23
	v_cmp_eq_u32_e64 s[0:1], 0, v25
	v_lshl_add_u64 v[36:37], v[20:21], 0, v[18:19]
	s_waitcnt vmcnt(0)
	ds_write_b128 v34, v[116:119] offset:9216
	s_waitcnt lgkmcnt(0)
	s_barrier
	ds_read2st64_b32 v[0:1], v15 offset0:252 offset1:253
	s_waitcnt lgkmcnt(0)
	v_add_f32_e32 v0, 0, v0
	v_cndmask_b32_e64 v2, v0, 0, vcc
	v_add_f32_e32 v3, v1, v2
	v_cndmask_b32_e64 v25, v3, v2, s[0:1]
	ds_read2st64_b32 v[2:3], v15 offset0:254 offset1:255
	v_cmp_eq_u32_e64 s[0:1], 3, v23
	s_waitcnt lgkmcnt(0)
	v_add_f32_e32 v30, v2, v25
	v_cndmask_b32_e64 v38, v25, v30, s[0:1]
	v_add_f32_e32 v34, v27, v38
	v_add_f32_e32 v27, v4, v38
	v_add_f32_e32 v4, v9, v38
	v_lshlrev_b32_e32 v9, 1, v16
	v_add_f32_e32 v18, v12, v38
	v_or_b32_e32 v12, s6, v24
	v_sub_u32_e32 v9, v15, v9
	v_add_f32_e32 v35, v26, v38
	v_add_f32_e32 v30, v28, v38
	v_add_f32_e32 v28, v29, v38
	v_add_f32_e32 v26, v5, v38
	v_add_f32_e32 v25, v6, v38
	v_add_f32_e32 v21, v7, v38
	v_add_f32_e32 v20, v8, v38
	v_add_f32_e32 v19, v10, v38
	v_add_f32_e32 v5, v11, v38
	v_add_f32_e32 v6, v13, v38
	v_add_f32_e32 v8, v14, v38
	v_add_f32_e32 v7, v31, v38
	v_cmp_lt_i32_e64 s[0:1], s46, v12
	v_mov_b32_e32 v13, 0
	v_mad_u32_u24 v10, v23, s45, v9
	v_mov_b32_e32 v14, 0
	global_store_dword v[36:37], v35, off
	global_store_dword v[36:37], v34, off offset:256
	global_store_dword v[36:37], v30, off offset:512
	global_store_dword v[36:37], v28, off offset:768
	global_store_dword v[36:37], v27, off offset:1024
	global_store_dword v[36:37], v26, off offset:1280
	global_store_dword v[36:37], v25, off offset:1536
	global_store_dword v[36:37], v21, off offset:1792
	global_store_dword v[36:37], v20, off offset:2048
	global_store_dword v[36:37], v4, off offset:2304
	global_store_dword v[36:37], v19, off offset:2560
	global_store_dword v[36:37], v5, off offset:2816
	global_store_dword v[36:37], v18, off offset:3072
	global_store_dword v[36:37], v6, off offset:3328
	global_store_dword v[36:37], v8, off offset:3584
	global_store_dword v[36:37], v7, off offset:3840
	s_and_saveexec_b64 s[2:3], s[0:1]
	s_cbranch_execz .LBB0_165
	ds_read_u16 v9, v10 offset:9216
	s_waitcnt lgkmcnt(0)
	v_lshlrev_b32_e32 v14, 16, v9

.LBB0_266:
	s_and_b64 vcc, exec, s[0:1]
	s_cbranch_vccz .LBB0_339
	s_add_i32 s0, s2, 0xfffff7e0
	v_mov_b32_e32 v58, v177
	s_and_b32 s1, s2, 15
	s_lshr_b32 s0, s0, 4
	v_ashrrev_i32_e32 v20, 6, v58
	s_bfe_u32 s6, s2, 0x20002
	s_mulk_i32 s1, 0x82
	v_and_b32_e32 v3, 1, v20
	s_lshl_b32 s3, s0, 6
	s_mulk_i32 s6, 0x2080
	s_add_i32 s1, s1, s0
	v_bfe_u32 v18, v58, 5, 1
	v_ashrrev_i32_e32 v32, 7, v58
	s_add_i32 s6, s6, s3
	v_lshlrev_b32_e32 v2, 5, v3
	s_lshl_b32 s7, s1, 14
	v_readlane_b32 s8, v245, 36
	v_and_b32_e32 v17, 31, v58
	v_lshlrev_b32_e32 v19, 5, v32
	v_lshl_or_b32 v25, v18, 4, v2
	v_readlane_b32 s9, v245, 37
	s_add_u32 s0, s8, s7
	v_or_b32_e32 v0, v19, v17
	s_addc_u32 s1, s9, 0
	v_lshlrev_b32_e32 v178, 8, v25
	s_mul_i32 s16, s6, 0x1618
	v_lshl_add_u64 v[4:5], s[0:1], 0, v[178:179]
	v_ashrrev_i32_e32 v1, 31, v0
	v_and_b32_e32 v33, 63, v58
	v_lshl_add_u64 v[8:9], v[0:1], 2, v[4:5]
	s_and_b32 s8, s2, 3
	s_lshl_b64 s[0:1], s[16:17], 1
	s_barrier
	global_load_dword v24, v[8:9], off
	global_load_dword v23, v[8:9], off offset:256
	global_load_dword v22, v[8:9], off offset:512
	global_load_dword v21, v[8:9], off offset:768
	global_load_dword v16, v[8:9], off offset:1024
	global_load_dword v15, v[8:9], off offset:1280
	global_load_dword v14, v[8:9], off offset:1536
	global_load_dword v13, v[8:9], off offset:1792
	global_load_dword v12, v[8:9], off offset:2048
	global_load_dword v11, v[8:9], off offset:2304
	global_load_dword v10, v[8:9], off offset:2560
	global_load_dword v7, v[8:9], off offset:2816
	global_load_dword v6, v[8:9], off offset:3072
	global_load_dword v5, v[8:9], off offset:3328
	global_load_dword v4, v[8:9], off offset:3584
	global_load_dword v1, v[8:9], off offset:3840
	s_add_u32 s0, s56, s0
	v_mul_u32_u24_e32 v8, 0x1618, v33
	s_addc_u32 s1, s57, s1
	v_lshlrev_b32_e32 v178, 1, v8
	v_lshl_add_u64 v[8:9], s[0:1], 0, v[178:179]
	s_lshl_b32 s16, s8, 7
	s_lshl_b32 s8, s8, 8
	s_mov_b32 s9, s17
	v_lshlrev_b32_e32 v26, 3, v20
	v_lshl_add_u64 v[8:9], v[8:9], 0, s[8:9]
	v_ashrrev_i32_e32 v27, 31, v26
	v_lshl_add_u64 v[8:9], v[26:27], 1, v[8:9]
	s_mov_b64 s[8:9], 0x1410
	v_lshl_add_u64 v[30:31], v[8:9], 0, s[8:9]
	v_add_co_u32_e32 v8, vcc, s38, v8
	s_movk_i32 s8, 0x480
	s_nop 0
	v_addc_co_u32_e32 v9, vcc, 0, v9, vcc
	global_load_dwordx4 v[80:83], v[8:9], off offset:1040
	global_load_dwordx4 v[84:87], v[30:31], off offset:64
	global_load_dwordx4 v[88:91], v[30:31], off offset:128
	global_load_dwordx4 v[92:95], v[30:31], off offset:192
	v_mul_lo_u32 v20, v20, s8
	v_lshl_or_b32 v20, v33, 1, v20
	v_lshlrev_b32_e32 v34, 3, v58
	v_and_b32_e32 v8, 56, v34
	v_lshlrev_b32_e32 v178, 1, v8
	v_ashrrev_i32_e32 v8, 3, v58
	v_add_u32_e32 v9, 0x100, v58
	v_ashrrev_i32_e32 v9, 3, v9
	v_readlane_b32 s10, v245, 38
	v_readlane_b32 s11, v245, 39
	v_mov_b64_e32 v[112:113], s[0:1]
	v_mad_u64_u32 v[38:39], s[0:1], v8, s12, v[178:179]
	v_mad_i64_i32 v[26:27], s[0:1], v8, s13, v[112:113]
	v_lshl_add_u64 v[26:27], v[26:27], 0, s[16:17]
	v_lshl_add_u64 v[26:27], v[26:27], 0, v[178:179]
	v_add_co_u32_e32 v114, vcc, s38, v26
	s_nop 1
	v_addc_co_u32_e32 v115, vcc, 0, v27, vcc
	global_load_dwordx4 v[96:99], v[114:115], off offset:528
	global_load_dwordx4 v[100:103], v[114:115], off offset:16
	v_mad_u64_u32 v[36:37], s[0:1], v9, s12, v[178:179]
	v_mad_i64_i32 v[26:27], s[0:1], v9, s13, v[112:113]
	v_lshl_add_u64 v[26:27], v[26:27], 0, s[16:17]
	v_lshl_add_u64 v[26:27], v[26:27], 0, v[178:179]
	v_add_co_u32_e32 v116, vcc, s38, v26
	s_nop 1
	v_addc_co_u32_e32 v117, vcc, 0, v27, vcc
	global_load_dwordx4 v[104:107], v[116:117], off offset:528
	global_load_dwordx4 v[108:111], v[116:117], off offset:16
	v_readlane_b32 s0, v245, 28
	v_readlane_b32 s1, v245, 29
	v_lshlrev_b32_e32 v26, 7, v8
	v_lshlrev_b32_e32 v27, 7, v9
	s_add_u32 s0, s0, s7
	s_addc_u32 s1, s1, 0
	v_lshl_add_u64 v[118:119], s[0:1], 0, v[178:179]
	v_add_u32_e32 v28, 0x200, v58
	v_ashrrev_i32_e32 v28, 3, v28
	v_lshlrev_b32_e32 v28, 7, v28
	v_add_u32_e32 v29, 0x300, v58
	v_ashrrev_i32_e32 v29, 3, v29
	v_lshlrev_b32_e32 v29, 7, v29
	v_ashrrev_i32_e32 v137, 31, v26
	v_mov_b32_e32 v136, v26
	v_lshl_add_u64 v[136:137], v[118:119], 0, v[136:137]
	global_load_dwordx4 v[120:123], v[136:137], off
	v_ashrrev_i32_e32 v137, 31, v27
	v_mov_b32_e32 v136, v27
	v_lshl_add_u64 v[136:137], v[118:119], 0, v[136:137]
	global_load_dwordx4 v[124:127], v[136:137], off
	v_ashrrev_i32_e32 v137, 31, v28
	v_mov_b32_e32 v136, v28
	v_lshl_add_u64 v[136:137], v[118:119], 0, v[136:137]
	global_load_dwordx4 v[128:131], v[136:137], off
	v_ashrrev_i32_e32 v137, 31, v29
	v_mov_b32_e32 v136, v29
	v_lshl_add_u64 v[136:137], v[118:119], 0, v[136:137]
	global_load_dwordx4 v[132:135], v[136:137], off
	s_waitcnt vmcnt(11)
	ds_write_b16 v20, v80 offset:18432
	ds_write_b16_d16_hi v20, v80 offset:18576
	ds_write_b16 v20, v81 offset:18720
	ds_write_b16_d16_hi v20, v81 offset:18864
	ds_write_b16 v20, v82 offset:19008
	ds_write_b16_d16_hi v20, v82 offset:19152
	ds_write_b16 v20, v83 offset:19296
	ds_write_b16_d16_hi v20, v83 offset:19440
	s_waitcnt vmcnt(10)
	ds_write_b16 v20, v84 offset:23040
	ds_write_b16_d16_hi v20, v84 offset:23184
	ds_write_b16 v20, v85 offset:23328
	ds_write_b16_d16_hi v20, v85 offset:23472
	ds_write_b16 v20, v86 offset:23616
	ds_write_b16_d16_hi v20, v86 offset:23760
	ds_write_b16 v20, v87 offset:23904
	ds_write_b16_d16_hi v20, v87 offset:24048
	s_waitcnt vmcnt(9)
	ds_write_b16 v20, v88 offset:27648
	ds_write_b16_d16_hi v20, v88 offset:27792
	ds_write_b16 v20, v89 offset:27936
	ds_write_b16_d16_hi v20, v89 offset:28080
	ds_write_b16 v20, v90 offset:28224
	ds_write_b16_d16_hi v20, v90 offset:28368
	ds_write_b16 v20, v91 offset:28512
	ds_write_b16_d16_hi v20, v91 offset:28656
	s_waitcnt vmcnt(8)
	ds_write_b16 v20, v92 offset:32256
	ds_write_b16_d16_hi v20, v92 offset:32400
	ds_write_b16 v20, v93 offset:32544
	ds_write_b16_d16_hi v20, v93 offset:32688
	ds_write_b16 v20, v94 offset:32832
	ds_write_b16_d16_hi v20, v94 offset:32976
	ds_write_b16 v20, v95 offset:33120
	ds_write_b16_d16_hi v20, v95 offset:33264
	s_nop 1
	v_mul_u32_u24_e32 v20, 0x48, v25
	v_add_lshl_u32 v20, v20, v0, 1
	s_waitcnt vmcnt(7)
	ds_write_b128 v38, v[96:99] offset:9216
	s_waitcnt vmcnt(6)
	ds_write_b128 v38, v[100:103]
	s_waitcnt vmcnt(5)
	ds_write_b128 v36, v[104:107] offset:9216
	s_waitcnt vmcnt(4)
	ds_write_b128 v36, v[108:111]
	s_waitcnt lgkmcnt(0)
	s_barrier
	ds_read_u16 v27, v20
	v_or_b32_e32 v26, s3, v25
	v_cmp_lt_u32_e32 vcc, s46, v26
	v_mov_b32_e32 v25, 0
	v_mov_b32_e32 v26, 0
	s_and_saveexec_b64 s[0:1], vcc
	s_cbranch_execz .LBB0_269
	ds_read_u16 v26, v20 offset:9216
	s_waitcnt lgkmcnt(0)
	v_lshlrev_b32_e32 v26, 16, v26

.LBB0_299:
	s_or_b64 exec, exec, s[0:1]
	v_add_f32_e32 v1, 0, v1
	v_mul_f32_e32 v6, 0x3fb8aa3b, v1
	v_exp_f32_e32 v6, v6
	v_mul_f32_e32 v1, 0xbfb8aa3b, v1
	s_waitcnt lgkmcnt(1)
	v_lshlrev_b32_e32 v4, 16, v4
	v_exp_f32_e32 v1, v1
	v_mul_f32_e32 v4, 0x3e000000, v4
	v_mul_f32_e32 v4, v6, v4
	v_bfe_u32 v6, v4, 16, 1
	v_readlane_b32 s68, v245, 20
	v_add3_u32 v4, v4, v6, s49
	v_mul_f32_e32 v1, v1, v5
	v_readlane_b32 s76, v245, 28
	ds_write_b16_d16_hi v20, v4 offset:2160
	v_bfe_u32 v4, v1, 16, 1
	v_readlane_b32 s77, v245, 29
	s_add_u32 s0, s76, s7
	v_add3_u32 v1, v1, v4, s49
	s_addc_u32 s1, s77, 0
	v_lshl_add_u64 v[10:11], s[0:1], 0, v[178:179]
	v_mad_u64_u32 v[12:13], s[0:1], v8, s12, v[178:179]
	ds_write_b16_d16_hi v20, v1 offset:11376
	v_add_u32_e32 v1, 0x200, v58
	v_ashrrev_i32_e32 v1, 3, v1
	v_cmp_le_i32_e32 vcc, v32, v3
	v_or_b32_e32 v60, v2, v17
	v_readlane_b32 s69, v245, 21
	v_readlane_b32 s70, v245, 22
	v_readlane_b32 s71, v245, 23
	v_readlane_b32 s72, v245, 24
	v_readlane_b32 s73, v245, 25
	v_readlane_b32 s74, v245, 26
	v_readlane_b32 s75, v245, 27
	v_readlane_b32 s78, v245, 30
	v_readlane_b32 s79, v245, 31
	v_readlane_b32 s80, v245, 32
	v_readlane_b32 s81, v245, 33
	v_readlane_b32 s82, v245, 34
	v_readlane_b32 s83, v245, 35
	s_waitcnt vmcnt(3)
	ds_write_b128 v12, v[120:123] offset:46080
	v_mad_u64_u32 v[8:9], s[0:1], v9, s12, v[178:179]
	s_waitcnt vmcnt(2)
	ds_write_b128 v8, v[124:127] offset:46080
	v_mad_u64_u32 v[8:9], s[0:1], v1, s12, v[178:179]
	v_add_u32_e32 v1, 0x300, v58
	v_ashrrev_i32_e32 v1, 3, v1
	s_waitcnt vmcnt(1)
	ds_write_b128 v8, v[128:131] offset:46080
	v_mad_u64_u32 v[8:9], s[0:1], v1, s12, v[178:179]
	v_lshlrev_b32_e32 v1, 3, v18
	v_lshlrev_b32_e32 v16, 1, v1
	s_waitcnt vmcnt(0)
	ds_write_b128 v8, v[132:135] offset:46080
	s_waitcnt lgkmcnt(0)
	s_barrier
	s_and_saveexec_b64 s[0:1], vcc
	s_xor_b64 s[0:1], exec, s[0:1]
	s_cbranch_execz .LBB0_301
	v_mad_u64_u32 v[28:29], s[8:9], v0, s12, v[16:17]
	ds_read_b128 v[4:7], v28 offset:9216
	v_or_b32_e32 v60, v2, v17
	v_mad_u32_u24 v29, v60, s12, v16
	ds_read_b128 v[0:3], v29
	ds_read_b128 v[20:23], v28 offset:9248
	ds_read_b128 v[24:27], v29 offset:32
	s_waitcnt lgkmcnt(2)
	v_mfma_f32_32x32x16_bf16 v[0:15], v[4:7], v[0:3], 0
	s_waitcnt lgkmcnt(0)
	v_mfma_f32_32x32x16_bf16 v[0:15], v[20:23], v[24:27], v[0:15]
	ds_read_b128 v[20:23], v28 offset:9280
	ds_read_b128 v[24:27], v29 offset:64
	s_waitcnt lgkmcnt(0)
	v_mfma_f32_32x32x16_bf16 v[0:15], v[20:23], v[24:27], v[0:15]
	ds_read_b128 v[22:25], v28 offset:9312
	ds_read_b128 v[26:29], v29 offset:96
	v_mul_u32_u24_e32 v20, 0x90, v60
	s_waitcnt lgkmcnt(0)
	v_mfma_f32_32x32x16_bf16 v[0:15], v[22:25], v[26:29], v[0:15]
